# version 97 plus L2 warm-up: sixteen dword LDS-DMA touches of the residual tile's lines issued in the residual loop's last K-iteration
# baseline (speedup 1.0000x reference)
; #define PG8_STAGE(bufoff, gbase, voff) do { _Pragma("unroll") for (int _i = 0; _i < 2; ++_i) \
;         __builtin_amdgcn_global_load_lds((const unsigned*)((const char*)(gbase) + (voff)[_i]), (PG8_LAS unsigned*)(lds + (bufoff) + ldsw + _i * 8192), 16, 0, 0); } while (0)
; #define PG8_LDA(dst, b, h) do { _Pragma("unroll") for (int m = 0; m < 4; ++m) _Pragma("unroll") for (int k = 0; k < 2; ++k) dst[m][k] = *(const PG8_LAS bf16x8*)(lds + PG8_SA(b, h) + aoff + m * 2048 + k * 1024); } while (0)
; #define PG8_MMA(ai, bj, At, Bt) do { __builtin_amdgcn_s_setprio(1); _Pragma("unroll") for (int m = 0; m < 4; ++m) _Pragma("unroll") for (int n = 0; n < 2; ++n) _Pragma("unroll") for (int k = 0; k < 2; ++k) \
;         acc[ai][bj][m][n] = __builtin_amdgcn_mfma_f32_16x16x32_bf16(Bt[n][k], At[m][k], acc[ai][bj][m][n], 0, 0, 0); __builtin_amdgcn_s_setprio(0); } while (0)
; #define PG8_WAIT_V(n) asm volatile("s_waitcnt vmcnt(" #n ")" ::: "memory")
; #define PG8_WAIT_L(n) asm volatile("s_waitcnt lgkmcnt(" #n ")" ::: "memory")
; #define PG8_BAR __builtin_amdgcn_s_barrier()
; #define PG8_SCHED __builtin_amdgcn_sched_barrier(0)
; template <class Epi, class Sched, bool ALIGN_EPI = false, bool SP2 = false>
; __device__ __forceinline__ void gemm_phase(PG8_LAS unsigned char* lds, const Gemm g, const Sched& S, const Epi& E, const int tid_in) {
;     ...
;             PG8_LDA(At, 0, 1); PG8_STAGE(PG8_SB(0, 0), b2, voffB); PG8_STAGE(PG8_SB(0, 1), b2 + hstep, voffB); PG8_STAGE(PG8_SA(0, 0), a2, voffA);
;             PG8_WAIT_V(8); PG8_WAIT_L(0); PG8_BAR; PG8_MMA(1, 0, At, B0); PG8_MMA(1, 1, At, B1); PG8_BAR; PG8_SCHED;
;     __device__ __forceinline__ void operator()(const f32x4 (&acc)[2][2][4][2], const Unit& u, int wr, int wc, int fr, int fq) const {
;     ...
;                 for (int bj = 0; bj < 2; ++bj) xv[ai][m][bj] = *(const u32x4*)(xb + (size_t)(row0 + ai * HALF + m * 16) * 1024 + col0 + bj * HALF);
.Lrt_skip_1:
	v_lshl_or_b32 v214, s49, 8, v248
	v_ashrrev_i32_e32 v215, 31, v214
	v_lshlrev_b64 v[214:215], 1, v[214:215]
	v_lshl_add_u64 v[214:215], s[84:85], 0, v[214:215]
	v_lshl_add_u32 v216, s50, 8, v246
	v_ashrrev_i32_e32 v217, 31, v216
	v_lshlrev_b64 v[216:217], 11, v[216:217]
	v_lshl_add_u64 v[214:215], v[214:215], 0, v[216:217]
	global_load_lds_dword v[214:215], off
	global_load_lds_dword v[214:215], off offset:256
	s_mov_b64 s[52:53], 0x8000
	v_lshl_add_u64 v[216:217], v[214:215], 0, s[52:53]
	global_load_lds_dword v[216:217], off
	global_load_lds_dword v[216:217], off offset:256
	s_mov_b64 s[52:53], 0x10000
	v_lshl_add_u64 v[216:217], v[214:215], 0, s[52:53]
	global_load_lds_dword v[216:217], off
	global_load_lds_dword v[216:217], off offset:256
	s_mov_b64 s[52:53], 0x18000
	v_lshl_add_u64 v[216:217], v[214:215], 0, s[52:53]
	global_load_lds_dword v[216:217], off
	global_load_lds_dword v[216:217], off offset:256
	s_mov_b64 s[52:53], 0x40000
	v_lshl_add_u64 v[216:217], v[214:215], 0, s[52:53]
	global_load_lds_dword v[216:217], off
	global_load_lds_dword v[216:217], off offset:256
	s_mov_b64 s[52:53], 0x48000
	v_lshl_add_u64 v[216:217], v[214:215], 0, s[52:53]
	global_load_lds_dword v[216:217], off
	global_load_lds_dword v[216:217], off offset:256
	s_mov_b64 s[52:53], 0x50000
	v_lshl_add_u64 v[216:217], v[214:215], 0, s[52:53]
	global_load_lds_dword v[216:217], off
	global_load_lds_dword v[216:217], off offset:256
	s_mov_b64 s[52:53], 0x58000
	v_lshl_add_u64 v[216:217], v[214:215], 0, s[52:53]
	global_load_lds_dword v[216:217], off
	global_load_lds_dword v[216:217], off offset:256
	s_waitcnt vmcnt(18)

; #define PG8_STAGE(bufoff, gbase, voff) do { _Pragma("unroll") for (int _i = 0; _i < 2; ++_i) \
;         __builtin_amdgcn_global_load_lds((const unsigned*)((const char*)(gbase) + (voff)[_i]), (PG8_LAS unsigned*)(lds + (bufoff) + ldsw + _i * 8192), 16, 0, 0); } while (0)
; #define PG8_LDA(dst, b, h) do { _Pragma("unroll") for (int m = 0; m < 4; ++m) _Pragma("unroll") for (int k = 0; k < 2; ++k) dst[m][k] = *(const PG8_LAS bf16x8*)(lds + PG8_SA(b, h) + aoff + m * 2048 + k * 1024); } while (0)
; #define PG8_LDB(dst, b, h) do { _Pragma("unroll") for (int n = 0; n < 2; ++n) _Pragma("unroll") for (int k = 0; k < 2; ++k) dst[n][k] = *(const PG8_LAS bf16x8*)(lds + PG8_SB(b, h) + boff + n * 2048 + k * 1024); } while (0)
; #define PG8_MMA(ai, bj, At, Bt) do { __builtin_amdgcn_s_setprio(1); _Pragma("unroll") for (int m = 0; m < 4; ++m) _Pragma("unroll") for (int n = 0; n < 2; ++n) _Pragma("unroll") for (int k = 0; k < 2; ++k) \
;         acc[ai][bj][m][n] = __builtin_amdgcn_mfma_f32_16x16x32_bf16(Bt[n][k], At[m][k], acc[ai][bj][m][n], 0, 0, 0); __builtin_amdgcn_s_setprio(0); } while (0)
; #define PG8_WAIT_V(n) asm volatile("s_waitcnt vmcnt(" #n ")" ::: "memory")
; #define PG8_WAIT_L(n) asm volatile("s_waitcnt lgkmcnt(" #n ")" ::: "memory")
; #define PG8_BAR __builtin_amdgcn_s_barrier()
; #define PG8_SCHED __builtin_amdgcn_sched_barrier(0)
; template <class Epi, class Sched, bool ALIGN_EPI = false, bool SP2 = false>
; __device__ __forceinline__ void gemm_phase(PG8_LAS unsigned char* lds, const Gemm g, const Sched& S, const Epi& E, const int tid_in) {
;     ...
;             PG8_LDB(B0, 1, 0); PG8_LDB(B1, 1, 1); PG8_SCHED; PG8_LDA(At, 1, 0); PG8_STAGE(PG8_SA(0, 1), a2 + hstep, voffA);
;             PG8_WAIT_V(8); PG8_WAIT_L(0); PG8_BAR; PG8_MMA(0, 0, At, B0); PG8_MMA(0, 1, At, B1); PG8_BAR; PG8_SCHED;
.Lrt_skip_2:
	s_waitcnt vmcnt(16)
